# seam weight conversion queue + nt hint on f32 weight loads
# speedup vs baseline: 1.0293x; 1.0101x over previous
; __device__ __forceinline__ void titem_load(const TItem& d, f32x4 (&v)[16], float (&gg)[16], int lane) {
; #pragma unroll
;     for (int i = 0; i < 16; ++i) { const int kk = 32 * (i >> 3) + 8 * (lane >> 4) + (i & 7); v[i] = *(const f32x4*)(d.src + (size_t)kk * d.N + (lane & 15) * 4); gg[i] = d.g ? d.g[kk] : 1.f; }
; }
.LBB0_23:
	s_lshr_b32 s30, s23, 6
	v_cvt_f32_i32_e32 v2, s30
	s_sext_i32_i16 s28, s43
	v_cvt_f32_i32_e32 v3, s28
	s_ashr_i32 s28, s28, 30
	v_rcp_iflag_f32_e32 v4, v2
	s_or_b32 s31, s28, 1
	v_mov_b32_e32 v63, 0
	v_mov_b32_e32 v161, 1.0
	v_mul_f32_e32 v4, v3, v4
	v_trunc_f32_e32 v4, v4
	v_fma_f32 v3, -v4, v2, v3
	v_cvt_i32_f32_e32 v4, v4
	v_cmp_ge_f32_e64 s[28:29], |v3|, v2
	s_and_b64 s[28:29], s[28:29], exec
	s_cselect_b32 s28, s31, 0
	v_readfirstlane_b32 s29, v4
	s_add_i32 s29, s29, s28
	s_sext_i32_i16 s28, s29
	s_mul_i32 s29, s29, s30
	s_lshl_b32 s34, s28, 6
	s_sub_i32 s29, s43, s29
	s_ashr_i32 s35, s34, 31
	s_sext_i32_i16 s40, s29
	s_mul_i32 s29, s35, s23
	s_mul_hi_u32 s31, s34, s23
	s_add_i32 s39, s31, s29
	s_mul_i32 s38, s34, s23
	s_lshl_b32 s30, s40, 6
	s_lshl_b64 s[38:39], s[38:39], 2
	s_add_u32 s29, s4, s38
	s_addc_u32 s38, s5, s39
	s_ashr_i32 s31, s30, 31
	s_lshl_b64 s[4:5], s[30:31], 2
	s_add_u32 s30, s29, s4
	v_mul_u32_u24_e32 v2, s23, v144
	s_addc_u32 s31, s38, s5
	v_lshlrev_b32_e32 v62, 2, v2
	v_lshl_add_u64 v[2:3], s[30:31], 0, v[62:63]
	v_lshlrev_b32_e32 v62, 2, v158
	v_lshl_add_u64 v[2:3], v[2:3], 0, v[62:63]
	global_load_dwordx4 v[2:5], v[2:3], off nt
	s_lshl_b64 s[4:5], s[34:35], 2
	s_add_u32 s34, s36, s4
	s_addc_u32 s35, s37, s5
	s_cmp_lg_u64 s[36:37], 0
	s_cselect_b64 s[38:39], -1, 0
	s_cmp_eq_u64 s[36:37], 0
	v_mov_b32_e32 v162, 1.0
	s_cbranch_scc1 .LBB0_25
	v_lshlrev_b32_e32 v6, 2, v144
	global_load_dword v162, v6, s[34:35]
.LBB0_25:
	v_mul_u32_u24_e32 v6, s23, v145
	v_lshlrev_b32_e32 v6, 2, v6
	v_mov_b32_e32 v7, v63
	v_lshl_add_u64 v[6:7], s[30:31], 0, v[6:7]
	v_lshl_add_u64 v[6:7], v[6:7], 0, v[62:63]
	global_load_dwordx4 v[6:9], v[6:7], off nt
	v_cndmask_b32_e64 v10, 0, 1, s[38:39]
	v_cmp_ne_u32_e64 s[4:5], 1, v10
	s_andn2_b64 vcc, exec, s[38:39]
	s_cbranch_vccnz .LBB0_27
	v_lshlrev_b32_e32 v10, 2, v144
	global_load_dword v161, v10, s[34:35] offset:4
.LBB0_27:
	v_mul_u32_u24_e32 v10, s23, v146
	v_mov_b32_e32 v63, 0
	v_lshlrev_b32_e32 v10, 2, v10
	v_mov_b32_e32 v11, v63
	v_lshl_add_u64 v[10:11], s[30:31], 0, v[10:11]
	v_lshl_add_u64 v[10:11], v[10:11], 0, v[62:63]
	global_load_dwordx4 v[10:13], v[10:11], off nt
	v_mov_b32_e32 v163, 1.0
	s_and_b64 vcc, exec, s[4:5]
	v_mov_b32_e32 v164, 1.0
	s_cbranch_vccnz .LBB0_29
	v_lshlrev_b32_e32 v14, 2, v144
	global_load_dword v164, v14, s[34:35] offset:8
.LBB0_29:
	v_mul_u32_u24_e32 v14, s23, v147
	v_lshlrev_b32_e32 v14, 2, v14
	v_mov_b32_e32 v15, v63
	v_lshl_add_u64 v[14:15], s[30:31], 0, v[14:15]
	v_lshl_add_u64 v[14:15], v[14:15], 0, v[62:63]
	global_load_dwordx4 v[14:17], v[14:15], off nt
	s_and_b64 vcc, exec, s[4:5]
	s_cbranch_vccnz .LBB0_31
	v_lshlrev_b32_e32 v18, 2, v144
	global_load_dword v163, v18, s[34:35] offset:12
.LBB0_31:
	v_mul_u32_u24_e32 v18, s23, v148
	v_mov_b32_e32 v63, 0
	v_lshlrev_b32_e32 v18, 2, v18
	v_mov_b32_e32 v19, v63
	v_lshl_add_u64 v[18:19], s[30:31], 0, v[18:19]
	v_lshl_add_u64 v[18:19], v[18:19], 0, v[62:63]
	global_load_dwordx4 v[18:21], v[18:19], off nt
	v_mov_b32_e32 v165, 1.0
	s_and_b64 vcc, exec, s[4:5]
	v_mov_b32_e32 v166, 1.0
	s_cbranch_vccnz .LBB0_33
	v_lshlrev_b32_e32 v22, 2, v144
	global_load_dword v166, v22, s[34:35] offset:16
.LBB0_33:
	v_mul_u32_u24_e32 v22, s23, v149
	v_lshlrev_b32_e32 v22, 2, v22
	v_mov_b32_e32 v23, v63
	v_lshl_add_u64 v[22:23], s[30:31], 0, v[22:23]
	v_lshl_add_u64 v[22:23], v[22:23], 0, v[62:63]
	global_load_dwordx4 v[22:25], v[22:23], off nt
	s_and_b64 vcc, exec, s[4:5]
	s_cbranch_vccnz .LBB0_35
	v_lshlrev_b32_e32 v26, 2, v144
	global_load_dword v165, v26, s[34:35] offset:20
.LBB0_35:
	v_mul_u32_u24_e32 v26, s23, v150
	v_mov_b32_e32 v63, 0
	v_lshlrev_b32_e32 v26, 2, v26
	v_mov_b32_e32 v27, v63
	v_lshl_add_u64 v[26:27], s[30:31], 0, v[26:27]
	v_lshl_add_u64 v[26:27], v[26:27], 0, v[62:63]
	global_load_dwordx4 v[26:29], v[26:27], off nt
	v_mov_b32_e32 v167, 1.0
	s_and_b64 vcc, exec, s[4:5]
	v_mov_b32_e32 v168, 1.0
	s_cbranch_vccnz .LBB0_37
	v_lshlrev_b32_e32 v30, 2, v144
	global_load_dword v168, v30, s[34:35] offset:24
; __device__ __forceinline__ void titem_load(const TItem& d, f32x4 (&v)[16], float (&gg)[16], int lane) {
; #pragma unroll
;     for (int i = 0; i < 16; ++i) { const int kk = 32 * (i >> 3) + 8 * (lane >> 4) + (i & 7); v[i] = *(const f32x4*)(d.src + (size_t)kk * d.N + (lane & 15) * 4); gg[i] = d.g ? d.g[kk] : 1.f; }
; }
.LBB0_37:
	v_mul_u32_u24_e32 v30, s23, v159
	v_lshlrev_b32_e32 v30, 2, v30
	v_mov_b32_e32 v31, v63
	v_lshl_add_u64 v[30:31], s[30:31], 0, v[30:31]
	v_lshl_add_u64 v[30:31], v[30:31], 0, v[62:63]
	global_load_dwordx4 v[30:33], v[30:31], off nt
	s_and_b64 vcc, exec, s[4:5]
	s_cbranch_vccnz .LBB0_39
	v_lshlrev_b32_e32 v34, 2, v159
	global_load_dword v167, v34, s[34:35]
.LBB0_39:
	v_mul_u32_u24_e32 v34, s23, v151
	v_mov_b32_e32 v63, 0
	v_lshlrev_b32_e32 v34, 2, v34
	v_mov_b32_e32 v35, v63
	v_lshl_add_u64 v[34:35], s[30:31], 0, v[34:35]
	v_lshl_add_u64 v[34:35], v[34:35], 0, v[62:63]
	global_load_dwordx4 v[34:37], v[34:35], off nt
	v_mov_b32_e32 v170, 1.0
	s_and_b64 vcc, exec, s[4:5]
	v_mov_b32_e32 v171, 1.0
	s_cbranch_vccnz .LBB0_41
	v_lshlrev_b32_e32 v38, 2, v144
	global_load_dword v171, v38, s[34:35] offset:128
.LBB0_41:
	v_mul_u32_u24_e32 v38, s23, v152
	v_lshlrev_b32_e32 v38, 2, v38
	v_mov_b32_e32 v39, v63
	v_lshl_add_u64 v[38:39], s[30:31], 0, v[38:39]
	v_lshl_add_u64 v[38:39], v[38:39], 0, v[62:63]
	global_load_dwordx4 v[38:41], v[38:39], off nt
	s_and_b64 vcc, exec, s[4:5]
	s_cbranch_vccnz .LBB0_43
	v_lshlrev_b32_e32 v42, 2, v144
	global_load_dword v170, v42, s[34:35] offset:132
.LBB0_43:
	v_mul_u32_u24_e32 v42, s23, v153
	v_mov_b32_e32 v63, 0
	v_lshlrev_b32_e32 v42, 2, v42
	v_mov_b32_e32 v43, v63
	v_lshl_add_u64 v[42:43], s[30:31], 0, v[42:43]
	v_lshl_add_u64 v[42:43], v[42:43], 0, v[62:63]
	global_load_dwordx4 v[42:45], v[42:43], off nt
	v_mov_b32_e32 v172, 1.0
	s_and_b64 vcc, exec, s[4:5]
	v_mov_b32_e32 v173, 1.0
	s_cbranch_vccnz .LBB0_45
	v_lshlrev_b32_e32 v46, 2, v144
	global_load_dword v173, v46, s[34:35] offset:136
.LBB0_45:
	v_mul_u32_u24_e32 v46, s23, v154
	v_lshlrev_b32_e32 v46, 2, v46
	v_mov_b32_e32 v47, v63
	v_lshl_add_u64 v[46:47], s[30:31], 0, v[46:47]
	v_lshl_add_u64 v[46:47], v[46:47], 0, v[62:63]
	global_load_dwordx4 v[46:49], v[46:47], off nt
	s_and_b64 vcc, exec, s[4:5]
	s_cbranch_vccnz .LBB0_47
	v_lshlrev_b32_e32 v50, 2, v144
	global_load_dword v172, v50, s[34:35] offset:140
.LBB0_47:
	v_mul_u32_u24_e32 v50, s23, v155
	v_mov_b32_e32 v63, 0
	v_lshlrev_b32_e32 v50, 2, v50
	v_mov_b32_e32 v51, v63
	v_lshl_add_u64 v[50:51], s[30:31], 0, v[50:51]
	v_lshl_add_u64 v[50:51], v[50:51], 0, v[62:63]
	global_load_dwordx4 v[50:53], v[50:51], off nt
	v_mov_b32_e32 v174, 1.0
	s_and_b64 vcc, exec, s[4:5]
	v_mov_b32_e32 v175, 1.0
	s_cbranch_vccnz .LBB0_49
	v_lshlrev_b32_e32 v54, 2, v144
	global_load_dword v175, v54, s[34:35] offset:144
.LBB0_49:
	v_mul_u32_u24_e32 v54, s23, v156
	v_lshlrev_b32_e32 v54, 2, v54
	v_mov_b32_e32 v55, v63
	v_lshl_add_u64 v[54:55], s[30:31], 0, v[54:55]
	v_lshl_add_u64 v[54:55], v[54:55], 0, v[62:63]
	global_load_dwordx4 v[54:57], v[54:55], off nt
	s_and_b64 vcc, exec, s[4:5]
	s_cbranch_vccnz .LBB0_51
	v_lshlrev_b32_e32 v58, 2, v144
	global_load_dword v174, v58, s[34:35] offset:148
.LBB0_51:
	v_mul_u32_u24_e32 v58, s23, v157
	v_mov_b32_e32 v63, 0
	v_lshlrev_b32_e32 v58, 2, v58
	v_mov_b32_e32 v59, v63
	v_lshl_add_u64 v[58:59], s[30:31], 0, v[58:59]
	v_lshl_add_u64 v[58:59], v[58:59], 0, v[62:63]
	global_load_dwordx4 v[58:61], v[58:59], off nt
	v_mov_b32_e32 v176, 1.0
	s_and_b64 vcc, exec, s[4:5]
	v_mov_b32_e32 v178, 1.0
	s_cbranch_vccnz .LBB0_53
	v_lshlrev_b32_e32 v64, 2, v144
	global_load_dword v178, v64, s[34:35] offset:152
.LBB0_53:
	v_mul_u32_u24_e32 v64, s23, v160
	v_lshlrev_b32_e32 v64, 2, v64
	v_mov_b32_e32 v65, v63
	v_lshl_add_u64 v[64:65], s[30:31], 0, v[64:65]
	v_lshl_add_u64 v[62:63], v[64:65], 0, v[62:63]
	global_load_dwordx4 v[62:65], v[62:63], off nt
	s_and_b64 vcc, exec, s[4:5]
	s_cbranch_vccnz .LBB0_55
	v_lshlrev_b32_e32 v66, 2, v160
	global_load_dword v176, v66, s[34:35]

; __device__ __forceinline__ void titem_load(const TItem& d, f32x4 (&v)[16], float (&gg)[16], int lane) {
; #pragma unroll
;     for (int i = 0; i < 16; ++i) { const int kk = 32 * (i >> 3) + 8 * (lane >> 4) + (i & 7); v[i] = *(const f32x4*)(d.src + (size_t)kk * d.N + (lane & 15) * 4); gg[i] = d.g ? d.g[kk] : 1.f; }
; }
; __global__ void __launch_bounds__(NWAVES * 64, 2) hybrid_fwd(Args args) {
;     ...
;                 if (itn < DEPTH * I_L) { d1 = decode(itn); titem_load(d1, vb, gb, lane); }
.LBB0_70:
	s_lshr_b32 s38, s59, 6
	v_cvt_f32_i32_e32 v66, s38
	s_sext_i32_i16 s36, s45
	v_cvt_f32_i32_e32 v67, s36
	s_ashr_i32 s36, s36, 30
	v_rcp_iflag_f32_e32 v68, v66
	s_or_b32 s39, s36, 1
	v_mul_u32_u24_e32 v70, s59, v145
	v_lshlrev_b32_e32 v127, 2, v144
	v_mul_f32_e32 v68, v67, v68
	v_trunc_f32_e32 v68, v68
	v_fma_f32 v67, -v68, v66, v67
	v_cvt_i32_f32_e32 v68, v68
	v_cmp_ge_f32_e64 s[36:37], |v67|, v66
	s_and_b64 s[36:37], s[36:37], exec
	s_cselect_b32 s36, s39, 0
	v_readfirstlane_b32 s37, v68
	s_add_i32 s37, s37, s36
	s_sext_i32_i16 s36, s37
	s_mul_i32 s37, s37, s38
	s_lshl_b32 s40, s36, 6
	s_sub_i32 s37, s45, s37
	s_ashr_i32 s41, s40, 31
	s_sext_i32_i16 s61, s37
	s_mul_i32 s37, s41, s59
	s_mul_hi_u32 s39, s40, s59
	s_add_i32 s45, s39, s37
	s_mul_i32 s44, s40, s59
	s_lshl_b32 s38, s61, 6
	s_lshl_b64 s[44:45], s[44:45], 2
	s_add_u32 s37, s4, s44
	s_addc_u32 s44, s5, s45
	s_ashr_i32 s39, s38, 31
	s_lshl_b64 s[4:5], s[38:39], 2
	s_add_u32 s38, s37, s4
	v_mul_u32_u24_e32 v66, s59, v144
	s_addc_u32 s39, s44, s5
	v_lshlrev_b32_e32 v130, 2, v66
	v_lshl_add_u64 v[66:67], s[38:39], 0, v[130:131]
	v_lshlrev_b32_e32 v130, 2, v158
	v_lshl_add_u64 v[66:67], v[66:67], 0, v[130:131]
	global_load_dwordx4 v[66:69], v[66:67], off nt
	s_lshl_b64 s[4:5], s[40:41], 2
	s_add_u32 s40, s42, s4
	s_addc_u32 s41, s43, s5
	s_cmp_lg_u64 s[42:43], 0
	s_cselect_b64 s[44:45], -1, 0
	s_cmp_eq_u64 s[42:43], 0
	s_cbranch_scc1 .LBB0_121
	global_load_dwordx2 v[132:133], v127, s[40:41]
	v_mul_hi_u32_u24_e32 v71, s59, v145
	s_cbranch_execnz .LBB0_73

; __device__ __forceinline__ void titem_load(const TItem& d, f32x4 (&v)[16], float (&gg)[16], int lane) {
; #pragma unroll
;     for (int i = 0; i < 16; ++i) { const int kk = 32 * (i >> 3) + 8 * (lane >> 4) + (i & 7); v[i] = *(const f32x4*)(d.src + (size_t)kk * d.N + (lane & 15) * 4); gg[i] = d.g ? d.g[kk] : 1.f; }
; }
; __global__ void __launch_bounds__(NWAVES * 64, 2) hybrid_fwd(Args args) {
;     ...
;                 if (itn < DEPTH * I_L) { d1 = decode(itn); titem_load(d1, vb, gb, lane); }
.LBB0_73:
	v_mul_u32_u24_e32 v72, s59, v146
	v_lshlrev_b32_e32 v72, 2, v72
	v_mov_b32_e32 v73, v131
	v_lshl_add_u64 v[70:71], v[70:71], 2, s[38:39]
	v_lshl_add_u64 v[72:73], s[38:39], 0, v[72:73]
	v_lshl_add_u64 v[70:71], v[70:71], 0, v[130:131]
	v_lshl_add_u64 v[72:73], v[72:73], 0, v[130:131]
	global_load_dwordx4 v[74:77], v[70:71], off nt
	s_nop 0
	global_load_dwordx4 v[70:73], v[72:73], off nt
	v_cndmask_b32_e64 v78, 0, 1, s[44:45]
	v_cmp_ne_u32_e64 s[4:5], 1, v78
	s_andn2_b64 vcc, exec, s[44:45]
	v_mul_u32_u24_e32 v78, s59, v147
	s_cbranch_vccnz .LBB0_122
	global_load_dwordx2 v[134:135], v127, s[40:41] offset:8
	v_mul_hi_u32_u24_e32 v79, s59, v147
	s_cbranch_execnz .LBB0_76

; __device__ __forceinline__ void titem_load(const TItem& d, f32x4 (&v)[16], float (&gg)[16], int lane) {
; #pragma unroll
;     for (int i = 0; i < 16; ++i) { const int kk = 32 * (i >> 3) + 8 * (lane >> 4) + (i & 7); v[i] = *(const f32x4*)(d.src + (size_t)kk * d.N + (lane & 15) * 4); gg[i] = d.g ? d.g[kk] : 1.f; }
; }
; __global__ void __launch_bounds__(NWAVES * 64, 2) hybrid_fwd(Args args) {
;     ...
;                 if (itn < DEPTH * I_L) { d1 = decode(itn); titem_load(d1, vb, gb, lane); }
.LBB0_76:
	v_mul_u32_u24_e32 v80, s59, v148
	v_lshlrev_b32_e32 v80, 2, v80
	v_mov_b32_e32 v81, v131
	v_lshl_add_u64 v[78:79], v[78:79], 2, s[38:39]
	v_lshl_add_u64 v[80:81], s[38:39], 0, v[80:81]
	v_lshl_add_u64 v[78:79], v[78:79], 0, v[130:131]
	v_lshl_add_u64 v[80:81], v[80:81], 0, v[130:131]
	global_load_dwordx4 v[82:85], v[78:79], off nt
	s_nop 0
	global_load_dwordx4 v[78:81], v[80:81], off nt
	s_and_b64 vcc, exec, s[4:5]
	v_mul_u32_u24_e32 v86, s59, v149
	s_cbranch_vccnz .LBB0_123
	global_load_dwordx2 v[136:137], v127, s[40:41] offset:16
	v_mul_hi_u32_u24_e32 v87, s59, v149
	s_cbranch_execnz .LBB0_79

; __device__ __forceinline__ void titem_load(const TItem& d, f32x4 (&v)[16], float (&gg)[16], int lane) {
; #pragma unroll
;     for (int i = 0; i < 16; ++i) { const int kk = 32 * (i >> 3) + 8 * (lane >> 4) + (i & 7); v[i] = *(const f32x4*)(d.src + (size_t)kk * d.N + (lane & 15) * 4); gg[i] = d.g ? d.g[kk] : 1.f; }
; }
; __global__ void __launch_bounds__(NWAVES * 64, 2) hybrid_fwd(Args args) {
;     ...
;                 if (itn < DEPTH * I_L) { d1 = decode(itn); titem_load(d1, vb, gb, lane); }
.LBB0_79:
	v_mul_u32_u24_e32 v88, s59, v150
	v_lshlrev_b32_e32 v88, 2, v88
	v_mov_b32_e32 v89, v131
	v_lshl_add_u64 v[86:87], v[86:87], 2, s[38:39]
	v_lshl_add_u64 v[88:89], s[38:39], 0, v[88:89]
	v_lshl_add_u64 v[86:87], v[86:87], 0, v[130:131]
	v_lshl_add_u64 v[88:89], v[88:89], 0, v[130:131]
	global_load_dwordx4 v[90:93], v[86:87], off nt
	s_nop 0
	global_load_dwordx4 v[86:89], v[88:89], off nt
	s_and_b64 vcc, exec, s[4:5]
	v_mul_u32_u24_e32 v94, s59, v159
	s_cbranch_vccnz .LBB0_124
	v_lshlrev_b32_e32 v95, 2, v159
	global_load_dword v183, v127, s[40:41] offset:24
	global_load_dword v184, v95, s[40:41]
	v_mul_hi_u32_u24_e32 v95, s59, v159
	s_cbranch_execnz .LBB0_82

; __device__ __forceinline__ void titem_load(const TItem& d, f32x4 (&v)[16], float (&gg)[16], int lane) {
; #pragma unroll
;     for (int i = 0; i < 16; ++i) { const int kk = 32 * (i >> 3) + 8 * (lane >> 4) + (i & 7); v[i] = *(const f32x4*)(d.src + (size_t)kk * d.N + (lane & 15) * 4); gg[i] = d.g ? d.g[kk] : 1.f; }
; }
; __global__ void __launch_bounds__(NWAVES * 64, 2) hybrid_fwd(Args args) {
;     ...
;                 if (itn < DEPTH * I_L) { d1 = decode(itn); titem_load(d1, vb, gb, lane); }
.LBB0_82:
	v_mul_u32_u24_e32 v96, s59, v151
	v_lshlrev_b32_e32 v96, 2, v96
	v_mov_b32_e32 v97, v131
	v_lshl_add_u64 v[94:95], v[94:95], 2, s[38:39]
	v_lshl_add_u64 v[96:97], s[38:39], 0, v[96:97]
	v_lshl_add_u64 v[94:95], v[94:95], 0, v[130:131]
	v_lshl_add_u64 v[96:97], v[96:97], 0, v[130:131]
	global_load_dwordx4 v[98:101], v[94:95], off nt
	s_nop 0
	global_load_dwordx4 v[94:97], v[96:97], off nt
	s_and_b64 vcc, exec, s[4:5]
	v_mul_u32_u24_e32 v102, s59, v152
	s_cbranch_vccnz .LBB0_125
	global_load_dwordx2 v[138:139], v127, s[40:41] offset:128
	v_mul_hi_u32_u24_e32 v103, s59, v152
	s_cbranch_execnz .LBB0_85

; __device__ __forceinline__ void titem_load(const TItem& d, f32x4 (&v)[16], float (&gg)[16], int lane) {
; #pragma unroll
;     for (int i = 0; i < 16; ++i) { const int kk = 32 * (i >> 3) + 8 * (lane >> 4) + (i & 7); v[i] = *(const f32x4*)(d.src + (size_t)kk * d.N + (lane & 15) * 4); gg[i] = d.g ? d.g[kk] : 1.f; }
; }
; __global__ void __launch_bounds__(NWAVES * 64, 2) hybrid_fwd(Args args) {
;     ...
;                 if (itn < DEPTH * I_L) { d1 = decode(itn); titem_load(d1, vb, gb, lane); }
.LBB0_85:
	v_mul_u32_u24_e32 v104, s59, v153
	v_lshlrev_b32_e32 v104, 2, v104
	v_mov_b32_e32 v105, v131
	v_lshl_add_u64 v[102:103], v[102:103], 2, s[38:39]
	v_lshl_add_u64 v[104:105], s[38:39], 0, v[104:105]
	v_lshl_add_u64 v[102:103], v[102:103], 0, v[130:131]
	v_lshl_add_u64 v[104:105], v[104:105], 0, v[130:131]
	global_load_dwordx4 v[106:109], v[102:103], off nt
	s_nop 0
	global_load_dwordx4 v[102:105], v[104:105], off nt
	s_and_b64 vcc, exec, s[4:5]
	v_mul_u32_u24_e32 v110, s59, v154
	s_cbranch_vccnz .LBB0_126
	global_load_dwordx2 v[140:141], v127, s[40:41] offset:136
	v_mul_hi_u32_u24_e32 v111, s59, v154
	s_cbranch_execnz .LBB0_88

; __device__ __forceinline__ void titem_load(const TItem& d, f32x4 (&v)[16], float (&gg)[16], int lane) {
; #pragma unroll
;     for (int i = 0; i < 16; ++i) { const int kk = 32 * (i >> 3) + 8 * (lane >> 4) + (i & 7); v[i] = *(const f32x4*)(d.src + (size_t)kk * d.N + (lane & 15) * 4); gg[i] = d.g ? d.g[kk] : 1.f; }
; }
; __global__ void __launch_bounds__(NWAVES * 64, 2) hybrid_fwd(Args args) {
;     ...
;                 if (itn < DEPTH * I_L) { d1 = decode(itn); titem_load(d1, vb, gb, lane); }
.LBB0_88:
	v_mul_u32_u24_e32 v112, s59, v155
	v_lshlrev_b32_e32 v112, 2, v112
	v_mov_b32_e32 v113, v131
	v_lshl_add_u64 v[110:111], v[110:111], 2, s[38:39]
	v_lshl_add_u64 v[112:113], s[38:39], 0, v[112:113]
	v_lshl_add_u64 v[110:111], v[110:111], 0, v[130:131]
	v_lshl_add_u64 v[112:113], v[112:113], 0, v[130:131]
	global_load_dwordx4 v[114:117], v[110:111], off nt
	s_nop 0
	global_load_dwordx4 v[110:113], v[112:113], off nt
	s_and_b64 vcc, exec, s[4:5]
	v_mul_u32_u24_e32 v118, s59, v156
	s_cbranch_vccnz .LBB0_127
	global_load_dwordx2 v[142:143], v127, s[40:41] offset:144
	v_mul_hi_u32_u24_e32 v119, s59, v156
	s_cbranch_execnz .LBB0_91

; __device__ __forceinline__ void titem_load(const TItem& d, f32x4 (&v)[16], float (&gg)[16], int lane) {
; #pragma unroll
;     for (int i = 0; i < 16; ++i) { const int kk = 32 * (i >> 3) + 8 * (lane >> 4) + (i & 7); v[i] = *(const f32x4*)(d.src + (size_t)kk * d.N + (lane & 15) * 4); gg[i] = d.g ? d.g[kk] : 1.f; }
; }
; __global__ void __launch_bounds__(NWAVES * 64, 2) hybrid_fwd(Args args) {
;     ...
;                 if (itn < DEPTH * I_L) { d1 = decode(itn); titem_load(d1, vb, gb, lane); }
.LBB0_91:
	v_mul_u32_u24_e32 v120, s59, v157
	v_lshlrev_b32_e32 v120, 2, v120
	v_mov_b32_e32 v121, v131
	v_lshl_add_u64 v[118:119], v[118:119], 2, s[38:39]
	v_lshl_add_u64 v[120:121], s[38:39], 0, v[120:121]
	v_lshl_add_u64 v[118:119], v[118:119], 0, v[130:131]
	v_lshl_add_u64 v[120:121], v[120:121], 0, v[130:131]
	global_load_dwordx4 v[122:125], v[118:119], off nt
	s_nop 0
	global_load_dwordx4 v[118:121], v[120:121], off nt
	s_and_b64 vcc, exec, s[4:5]
	v_mul_u32_u24_e32 v126, s59, v160
	s_cbranch_vccnz .LBB0_128
	v_lshlrev_b32_e32 v128, 2, v160
	global_load_dword v185, v127, s[40:41] offset:152
	global_load_dword v186, v128, s[40:41]
	v_mul_hi_u32_u24_e32 v127, s59, v160
	s_cbranch_execnz .LBB0_94

; __device__ __forceinline__ void titem_load(const TItem& d, f32x4 (&v)[16], float (&gg)[16], int lane) {
; #pragma unroll
;     for (int i = 0; i < 16; ++i) { const int kk = 32 * (i >> 3) + 8 * (lane >> 4) + (i & 7); v[i] = *(const f32x4*)(d.src + (size_t)kk * d.N + (lane & 15) * 4); gg[i] = d.g ? d.g[kk] : 1.f; }
; }
; __global__ void __launch_bounds__(NWAVES * 64, 2) hybrid_fwd(Args args) {
;     ...
;                 if (itn < DEPTH * I_L) { d1 = decode(itn); titem_load(d1, vb, gb, lane); }
.LBB0_94:
	v_lshl_add_u64 v[126:127], v[126:127], 2, s[38:39]
	v_lshl_add_u64 v[126:127], v[126:127], 0, v[130:131]
	global_load_dwordx4 v[126:129], v[126:127], off nt
	s_ashr_i32 s37, s36, 31
	s_lshl_b64 s[4:5], s[36:37], 15
	s_add_u32 s34, s34, s4
	s_addc_u32 s35, s35, s5
	s_lshl_b32 s4, s61, 7
	s_or_b32 s40, s4, s60
